# Q-up epilogue: second row-norm (SSQ) load issued together with the first instead of after its vmcnt(0)
# baseline (speedup 1.0000x reference)
.LBB0_522:
	v_mbcnt_lo_u32_b32 v226, -1, 0
	v_mbcnt_hi_u32_b32 v226, -1, v226
	v_and_b32_e32 v226, 16, v226
	v_lshrrev_b32_e32 v227, 1, v226
	v_add_u32_e32 v226, v226, v227
	v_mov_b32_e32 v227, 0
	s_lshl_b32 s4, s66, 8
	v_mov_b32_e32 v106, v222
	v_mov_b32_e32 v157, v223
	s_add_i32 s4, s4, s41
	s_nop 0
	v_add_u32_e32 v186, s4, v106
	v_ashrrev_i32_e32 v187, 31, v186
	v_lshlrev_b64 v[184:185], 4, v[186:187]
	v_lshl_add_u64 v[106:107], s[90:91], 0, v[184:185]
	global_load_dwordx4 v[106:109], v[106:107], off
	v_add_u32_e32 v200, 16, v186
	v_ashrrev_i32_e32 v201, 31, v200
	v_lshlrev_b64 v[206:207], 4, v[200:201]
	v_lshl_add_u64 v[228:229], s[90:91], 0, v[206:207]
	global_load_dwordx4 v[228:231], v[228:229], off
	s_mov_b32 s4, 0x3b800000
	v_add_u32_e32 v202, 32, v186
	v_add_u32_e32 v158, 0xb0, v186
	v_ashrrev_i32_e32 v203, 31, v202
	v_add_u32_e32 v196, 48, v186
	v_ashrrev_i32_e32 v159, 31, v158
	v_lshlrev_b64 v[204:205], 4, v[202:203]
	v_ashrrev_i32_e32 v197, 31, v196
	v_add_u32_e32 v190, 0x80, v186
	v_lshlrev_b64 v[160:161], 4, v[158:159]
	v_lshlrev_b64 v[198:199], 4, v[196:197]
	v_ashrrev_i32_e32 v191, 31, v190
	v_add_u32_e32 v182, 0x90, v186
	v_lshlrev_b64 v[194:195], 4, v[190:191]
	v_ashrrev_i32_e32 v183, 31, v182
	v_add_u32_e32 v178, 0xa0, v186
	v_lshlrev_b64 v[188:189], 4, v[182:183]
	v_ashrrev_i32_e32 v179, 31, v178
	v_lshlrev_b64 v[180:181], 4, v[178:179]
	v_lshlrev_b32_e32 v208, 2, v157
	v_ashrrev_i32_e32 v209, 31, v208
	v_lshlrev_b64 v[164:165], 2, v[208:209]
	v_lshl_add_u64 v[162:163], s[78:79], 0, v[164:165]
	v_lshl_add_u64 v[164:165], s[80:81], 0, v[164:165]
	s_waitcnt vmcnt(0)
	v_mov_b32_e32 v110, v107
	v_mov_b32_e32 v111, v108
	v_mov_b32_e32 v107, v109
	v_pk_add_f32 v[110:111], v[110:111], v[106:107]
	v_mov_b32_e32 v106, v228
	v_mov_b32_e32 v107, v229
	v_mov_b32_e32 v108, v230
	v_mov_b32_e32 v109, v231
	v_mov_b32_e32 v112, v107
	v_mov_b32_e32 v113, v108
	v_mov_b32_e32 v107, v109
	v_pk_add_f32 v[106:107], v[112:113], v[106:107]
	v_mov_b32_e32 v109, v110
	v_mov_b32_e32 v108, v106
	v_mov_b32_e32 v110, v107
	v_pk_add_f32 v[106:107], v[108:109], v[110:111]
	v_lshl_add_u64 v[110:111], s[90:91], 0, v[160:161]
	v_pk_fma_f32 v[192:193], v[106:107], s[4:5], v[166:167] op_sel_hi:[1,0,0]
	global_load_dwordx4 v[110:113], v[110:111], off
	v_mul_f32_e32 v106, 0x4b800000, v193
	v_cmp_gt_f32_e64 s[4:5], s29, v193
	v_cmp_gt_f32_e32 vcc, s29, v192
	s_nop 0
	v_cndmask_b32_e64 v106, v193, v106, s[4:5]
	v_rsq_f32_e32 v106, v106
	s_nop 0
	v_mul_f32_e32 v107, 0x45800000, v106
	v_cndmask_b32_e64 v106, v106, v107, s[4:5]
	v_mul_f32_e32 v156, 0x3e16c740, v106
	v_lshl_add_u64 v[106:107], s[90:91], 0, v[204:205]
	global_load_dwordx4 v[138:141], v[106:107], off
	v_lshl_add_u64 v[106:107], s[90:91], 0, v[198:199]
	global_load_dwordx4 v[142:145], v[106:107], off
	v_lshl_add_u64 v[106:107], s[90:91], 0, v[194:195]
	global_load_dwordx4 v[130:133], v[106:107], off
	v_lshl_add_u64 v[106:107], s[90:91], 0, v[188:189]
	global_load_dwordx4 v[134:137], v[106:107], off
	v_lshl_add_u64 v[106:107], s[90:91], 0, v[180:181]
	global_load_dwordx4 v[106:109], v[106:107], off
	s_lshl_b32 s4, s65, 8
	s_or_b32 s4, s4, s62
	s_ashr_i32 s15, s4, 5
	s_mul_hi_i32 s5, s15, 0x55555556
	s_lshr_b32 s6, s5, 31
	s_add_i32 s5, s5, s6
	s_mul_i32 s5, s5, 3
	s_sub_i32 s5, s15, s5
	s_cmp_eq_u32 s5, 2
	v_pk_mul_f32 v[210:211], v[152:153], v[156:157] op_sel_hi:[1,0]
	v_lshlrev_b64 v[152:153], 2, v[184:185]
	s_cselect_b64 s[58:59], -1, 0
	s_cmp_lg_u32 s5, 2
	v_pk_mul_f32 v[148:149], v[148:149], v[156:157] op_sel_hi:[1,0]
	v_pk_mul_f32 v[146:147], v[146:147], v[156:157] op_sel_hi:[1,0]
	v_pk_mul_f32 v[212:213], v[150:151], v[156:157] op_sel_hi:[1,0]
	v_lshl_add_u64 v[150:151], v[162:163], 0, v[152:153]
	v_lshl_add_u64 v[184:185], v[164:165], 0, v[152:153]
	s_cbranch_scc1 .LBB0_524
	global_load_dwordx4 v[168:171], v[184:185], off
	global_load_dwordx4 v[172:175], v[150:151], off
	s_waitcnt vmcnt(1)
	v_pk_mul_f32 v[152:153], v[210:211], v[170:171]
	v_pk_mul_f32 v[176:177], v[212:213], v[168:169]
	v_pk_mul_f32 v[170:171], v[148:149], v[170:171]
	v_pk_mul_f32 v[168:169], v[146:147], v[168:169]
	s_waitcnt vmcnt(0)
	v_pk_fma_f32 v[148:149], v[148:149], v[174:175], v[152:153] neg_lo:[0,0,1] neg_hi:[0,0,1]
	v_pk_fma_f32 v[146:147], v[146:147], v[172:173], v[176:177] neg_lo:[0,0,1] neg_hi:[0,0,1]
	v_pk_fma_f32 v[210:211], v[210:211], v[174:175], v[170:171]
	v_pk_fma_f32 v[212:213], v[212:213], v[172:173], v[168:169]
